# GEMM units zeroed their 128 accumulators twice per unit: second copy removed (12 GEMM instances)
# speedup vs baseline: 1.0002x; 1.0002x over previous
; template <class Epi, class Sched, bool ALIGN_EPI = false, bool SP2 = false>
; __device__ __forceinline__ void gemm_phase(PG8_LAS unsigned char* lds, const Gemm g, const Sched& S, const Epi& E) {
;     ...
;     f32x4 acc[2][2][4][2];
; #pragma unroll
;     for (int a = 0; a < 2; ++a)
; #pragma unroll
;         for (int b = 0; b < 2; ++b)
; #pragma unroll
;             for (int m = 0; m < 4; ++m)
; #pragma unroll
;                 for (int n = 0; n < 2; ++n) acc[a][b][m][n] = (f32x4){0.f, 0.f, 0.f, 0.f};
.LBB0_497:
	v_mov_b32_e32 v127, 0
	s_andn2_b64 vcc, exec, s[48:49]
	v_mov_b32_e32 v126, v127
	v_mov_b32_e32 v125, v127
	v_mov_b32_e32 v124, v127
	v_mov_b32_e32 v123, v127
	v_mov_b32_e32 v122, v127
	v_mov_b32_e32 v121, v127
	v_mov_b32_e32 v120, v127
	v_mov_b32_e32 v115, v127
	v_mov_b32_e32 v114, v127
	v_mov_b32_e32 v113, v127
	v_mov_b32_e32 v112, v127
	v_mov_b32_e32 v107, v127
	v_mov_b32_e32 v106, v127
	v_mov_b32_e32 v105, v127
	v_mov_b32_e32 v104, v127
	v_mov_b32_e32 v97, v127
	v_mov_b32_e32 v96, v127
	v_mov_b32_e32 v95, v127
	v_mov_b32_e32 v94, v127
	v_mov_b32_e32 v89, v127
	v_mov_b32_e32 v88, v127
	v_mov_b32_e32 v87, v127
	v_mov_b32_e32 v86, v127
	v_mov_b32_e32 v81, v127
	v_mov_b32_e32 v80, v127
	v_mov_b32_e32 v79, v127
	v_mov_b32_e32 v78, v127
	v_mov_b32_e32 v73, v127
	v_mov_b32_e32 v72, v127
	v_mov_b32_e32 v71, v127
	v_mov_b32_e32 v70, v127
	v_mov_b32_e32 v131, v127
	v_mov_b32_e32 v130, v127
	v_mov_b32_e32 v129, v127
	v_mov_b32_e32 v128, v127
	v_mov_b32_e32 v119, v127
	v_mov_b32_e32 v118, v127
	v_mov_b32_e32 v117, v127
	v_mov_b32_e32 v116, v127
	v_mov_b32_e32 v111, v127
	v_mov_b32_e32 v110, v127
	v_mov_b32_e32 v109, v127
	v_mov_b32_e32 v108, v127
	v_mov_b32_e32 v103, v127
	v_mov_b32_e32 v102, v127
	v_mov_b32_e32 v101, v127
	v_mov_b32_e32 v100, v127
	v_mov_b32_e32 v93, v127
	v_mov_b32_e32 v92, v127
	v_mov_b32_e32 v91, v127
	v_mov_b32_e32 v90, v127
	v_mov_b32_e32 v85, v127
	v_mov_b32_e32 v84, v127
	v_mov_b32_e32 v83, v127
	v_mov_b32_e32 v82, v127
	v_mov_b32_e32 v77, v127
	v_mov_b32_e32 v76, v127
	v_mov_b32_e32 v75, v127
	v_mov_b32_e32 v74, v127
	v_mov_b32_e32 v69, v127
	v_mov_b32_e32 v68, v127
	v_mov_b32_e32 v67, v127
	v_mov_b32_e32 v66, v127
	v_mov_b32_e32 v65, v127
	v_mov_b32_e32 v64, v127
	v_mov_b32_e32 v63, v127
	v_mov_b32_e32 v62, v127
	v_mov_b32_e32 v57, v127
	v_mov_b32_e32 v56, v127
	v_mov_b32_e32 v55, v127
	v_mov_b32_e32 v54, v127
	v_mov_b32_e32 v49, v127
	v_mov_b32_e32 v48, v127
	v_mov_b32_e32 v47, v127
	v_mov_b32_e32 v46, v127
	v_mov_b32_e32 v41, v127
	v_mov_b32_e32 v40, v127
	v_mov_b32_e32 v39, v127
	v_mov_b32_e32 v38, v127
	v_mov_b32_e32 v33, v127
	v_mov_b32_e32 v32, v127
	v_mov_b32_e32 v31, v127
	v_mov_b32_e32 v30, v127
	v_mov_b32_e32 v25, v127
	v_mov_b32_e32 v24, v127
	v_mov_b32_e32 v23, v127
	v_mov_b32_e32 v22, v127
	v_mov_b32_e32 v17, v127
	v_mov_b32_e32 v16, v127
	v_mov_b32_e32 v15, v127
	v_mov_b32_e32 v14, v127
	v_mov_b32_e32 v9, v127
	v_mov_b32_e32 v8, v127
	v_mov_b32_e32 v7, v127
	v_mov_b32_e32 v6, v127
	v_mov_b32_e32 v61, v127
	v_mov_b32_e32 v60, v127
	v_mov_b32_e32 v59, v127
	v_mov_b32_e32 v58, v127
	v_mov_b32_e32 v53, v127
	v_mov_b32_e32 v52, v127
	v_mov_b32_e32 v51, v127
	v_mov_b32_e32 v50, v127
	v_mov_b32_e32 v45, v127
	v_mov_b32_e32 v44, v127
	v_mov_b32_e32 v43, v127
	v_mov_b32_e32 v42, v127
	v_mov_b32_e32 v37, v127
	v_mov_b32_e32 v36, v127
	v_mov_b32_e32 v35, v127
	v_mov_b32_e32 v34, v127
	v_mov_b32_e32 v29, v127
	v_mov_b32_e32 v28, v127
	v_mov_b32_e32 v27, v127
	v_mov_b32_e32 v26, v127
	v_mov_b32_e32 v21, v127
	v_mov_b32_e32 v20, v127
	v_mov_b32_e32 v19, v127
	v_mov_b32_e32 v18, v127
	v_mov_b32_e32 v13, v127
	v_mov_b32_e32 v12, v127
	v_mov_b32_e32 v11, v127
	v_mov_b32_e32 v10, v127
	v_mov_b32_e32 v5, v127
	v_mov_b32_e32 v4, v127
	v_mov_b32_e32 v3, v127
	v_mov_b32_e32 v2, v127
	s_cbranch_vccnz .LBB0_500
	s_add_u32 s2, s36, 0x80
	s_addc_u32 s3, s37, 0
	s_add_u32 s4, s34, 0x100
	s_addc_u32 s16, s35, 0
	s_mov_b32 s17, 0

; template <class Epi, class Sched, bool ALIGN_EPI = false, bool SP2 = false>
; __device__ __forceinline__ void gemm_phase(PG8_LAS unsigned char* lds, const Gemm g, const Sched& S, const Epi& E) {
;     ...
;         if (!has_next) break;
; #pragma unroll
;         for (int a = 0; a < 2; ++a)
; #pragma unroll
;             for (int b = 0; b < 2; ++b)
; #pragma unroll
;                 for (int m = 0; m < 4; ++m)
; #pragma unroll
;                     for (int n = 0; n < 2; ++n) acc[a][b][m][n] = (f32x4){0.f, 0.f, 0.f, 0.f};
;         cur = nxt; cA = nA; cB = nB; ++ui;
.LBB0_519:
	v_mov_b32_e32 v127, 0
	s_andn2_b64 vcc, exec, s[46:47]
	v_mov_b32_e32 v126, v127
	v_mov_b32_e32 v125, v127
	v_mov_b32_e32 v124, v127
	v_mov_b32_e32 v131, v127
	v_mov_b32_e32 v130, v127
	v_mov_b32_e32 v129, v127
	v_mov_b32_e32 v128, v127
	v_mov_b32_e32 v115, v127
	v_mov_b32_e32 v114, v127
	v_mov_b32_e32 v113, v127
	v_mov_b32_e32 v112, v127
	v_mov_b32_e32 v111, v127
	v_mov_b32_e32 v110, v127
	v_mov_b32_e32 v109, v127
	v_mov_b32_e32 v108, v127
	v_mov_b32_e32 v97, v127
	v_mov_b32_e32 v96, v127
	v_mov_b32_e32 v95, v127
	v_mov_b32_e32 v94, v127
	v_mov_b32_e32 v93, v127
	v_mov_b32_e32 v92, v127
	v_mov_b32_e32 v91, v127
	v_mov_b32_e32 v90, v127
	v_mov_b32_e32 v81, v127
	v_mov_b32_e32 v80, v127
	v_mov_b32_e32 v79, v127
	v_mov_b32_e32 v78, v127
	v_mov_b32_e32 v77, v127
	v_mov_b32_e32 v76, v127
	v_mov_b32_e32 v75, v127
	v_mov_b32_e32 v74, v127
	v_mov_b32_e32 v123, v127
	v_mov_b32_e32 v122, v127
	v_mov_b32_e32 v121, v127
	v_mov_b32_e32 v120, v127
	v_mov_b32_e32 v119, v127
	v_mov_b32_e32 v118, v127
	v_mov_b32_e32 v117, v127
	v_mov_b32_e32 v116, v127
	v_mov_b32_e32 v107, v127
	v_mov_b32_e32 v106, v127
	v_mov_b32_e32 v105, v127
	v_mov_b32_e32 v104, v127
	v_mov_b32_e32 v103, v127
	v_mov_b32_e32 v102, v127
	v_mov_b32_e32 v101, v127
	v_mov_b32_e32 v100, v127
	v_mov_b32_e32 v89, v127
	v_mov_b32_e32 v88, v127
	v_mov_b32_e32 v87, v127
	v_mov_b32_e32 v86, v127
	v_mov_b32_e32 v85, v127
	v_mov_b32_e32 v84, v127
	v_mov_b32_e32 v83, v127
	v_mov_b32_e32 v82, v127
	v_mov_b32_e32 v73, v127
	v_mov_b32_e32 v72, v127
	v_mov_b32_e32 v71, v127
	v_mov_b32_e32 v70, v127
	v_mov_b32_e32 v69, v127
	v_mov_b32_e32 v68, v127
	v_mov_b32_e32 v67, v127
	v_mov_b32_e32 v66, v127
	v_mov_b32_e32 v65, v127
	v_mov_b32_e32 v64, v127
	v_mov_b32_e32 v63, v127
	v_mov_b32_e32 v62, v127
	v_mov_b32_e32 v61, v127
	v_mov_b32_e32 v60, v127
	v_mov_b32_e32 v59, v127
	v_mov_b32_e32 v58, v127
	v_mov_b32_e32 v49, v127
	v_mov_b32_e32 v48, v127
	v_mov_b32_e32 v47, v127
	v_mov_b32_e32 v46, v127
	v_mov_b32_e32 v45, v127
	v_mov_b32_e32 v44, v127
	v_mov_b32_e32 v43, v127
	v_mov_b32_e32 v42, v127
	v_mov_b32_e32 v33, v127
	v_mov_b32_e32 v32, v127
	v_mov_b32_e32 v31, v127
	v_mov_b32_e32 v30, v127
	v_mov_b32_e32 v29, v127
	v_mov_b32_e32 v28, v127
	v_mov_b32_e32 v27, v127
	v_mov_b32_e32 v26, v127
	v_mov_b32_e32 v17, v127
	v_mov_b32_e32 v16, v127
	v_mov_b32_e32 v15, v127
	v_mov_b32_e32 v14, v127
	v_mov_b32_e32 v13, v127
	v_mov_b32_e32 v12, v127
	v_mov_b32_e32 v11, v127
	v_mov_b32_e32 v10, v127
	v_mov_b32_e32 v57, v127
	v_mov_b32_e32 v56, v127
	v_mov_b32_e32 v55, v127
	v_mov_b32_e32 v54, v127
	v_mov_b32_e32 v53, v127
	v_mov_b32_e32 v52, v127
	v_mov_b32_e32 v51, v127
	v_mov_b32_e32 v50, v127
	v_mov_b32_e32 v41, v127
	v_mov_b32_e32 v40, v127
	v_mov_b32_e32 v39, v127
	v_mov_b32_e32 v38, v127
	v_mov_b32_e32 v37, v127
	v_mov_b32_e32 v36, v127
	v_mov_b32_e32 v35, v127
	v_mov_b32_e32 v34, v127
	v_mov_b32_e32 v25, v127
	v_mov_b32_e32 v24, v127
	v_mov_b32_e32 v23, v127
	v_mov_b32_e32 v22, v127
	v_mov_b32_e32 v21, v127
	v_mov_b32_e32 v20, v127
	v_mov_b32_e32 v19, v127
	v_mov_b32_e32 v18, v127
	v_mov_b32_e32 v9, v127
	v_mov_b32_e32 v8, v127
	v_mov_b32_e32 v7, v127
	v_mov_b32_e32 v6, v127
	v_mov_b32_e32 v5, v127
	v_mov_b32_e32 v4, v127
	v_mov_b32_e32 v3, v127
	v_mov_b32_e32 v2, v127
	s_cbranch_vccnz .LBB0_522
	s_add_u32 s34, s34, 0x80
	s_addc_u32 s35, s35, 0
	s_add_u32 s4, s36, 0x100
	s_addc_u32 s16, s37, 0
	s_mov_b32 s17, 0

; template <class Epi, class Sched, bool ALIGN_EPI = false, bool SP2 = false>
; __device__ __forceinline__ void gemm_phase(PG8_LAS unsigned char* lds, const Gemm g, const Sched& S, const Epi& E) {
;     ...
;         if (!has_next) break;
; #pragma unroll
;         for (int a = 0; a < 2; ++a)
; #pragma unroll
;             for (int b = 0; b < 2; ++b)
; #pragma unroll
;                 for (int m = 0; m < 4; ++m)
; #pragma unroll
;                     for (int n = 0; n < 2; ++n) acc[a][b][m][n] = (f32x4){0.f, 0.f, 0.f, 0.f};
;         cur = nxt; cA = nA; cB = nB; ++ui;
.LBB0_874:
	v_mov_b32_e32 v131, 0
	s_andn2_b64 vcc, exec, s[50:51]
	v_mov_b32_e32 v130, v131
	v_mov_b32_e32 v129, v131
	v_mov_b32_e32 v128, v131
	v_mov_b32_e32 v127, v131
	v_mov_b32_e32 v126, v131
	v_mov_b32_e32 v125, v131
	v_mov_b32_e32 v124, v131
	v_mov_b32_e32 v115, v131
	v_mov_b32_e32 v114, v131
	v_mov_b32_e32 v113, v131
	v_mov_b32_e32 v112, v131
	v_mov_b32_e32 v111, v131
	v_mov_b32_e32 v110, v131
	v_mov_b32_e32 v109, v131
	v_mov_b32_e32 v108, v131
	v_mov_b32_e32 v97, v131
	v_mov_b32_e32 v96, v131
	v_mov_b32_e32 v95, v131
	v_mov_b32_e32 v94, v131
	v_mov_b32_e32 v93, v131
	v_mov_b32_e32 v92, v131
	v_mov_b32_e32 v91, v131
	v_mov_b32_e32 v90, v131
	v_mov_b32_e32 v81, v131
	v_mov_b32_e32 v80, v131
	v_mov_b32_e32 v79, v131
	v_mov_b32_e32 v78, v131
	v_mov_b32_e32 v77, v131
	v_mov_b32_e32 v76, v131
	v_mov_b32_e32 v75, v131
	v_mov_b32_e32 v74, v131
	v_mov_b32_e32 v123, v131
	v_mov_b32_e32 v122, v131
	v_mov_b32_e32 v121, v131
	v_mov_b32_e32 v120, v131
	v_mov_b32_e32 v119, v131
	v_mov_b32_e32 v118, v131
	v_mov_b32_e32 v117, v131
	v_mov_b32_e32 v116, v131
	v_mov_b32_e32 v107, v131
	v_mov_b32_e32 v106, v131
	v_mov_b32_e32 v105, v131
	v_mov_b32_e32 v104, v131
	v_mov_b32_e32 v103, v131
	v_mov_b32_e32 v102, v131
	v_mov_b32_e32 v101, v131
	v_mov_b32_e32 v100, v131
	v_mov_b32_e32 v89, v131
	v_mov_b32_e32 v88, v131
	v_mov_b32_e32 v87, v131
	v_mov_b32_e32 v86, v131
	v_mov_b32_e32 v85, v131
	v_mov_b32_e32 v84, v131
	v_mov_b32_e32 v83, v131
	v_mov_b32_e32 v82, v131
	v_mov_b32_e32 v73, v131
	v_mov_b32_e32 v72, v131
	v_mov_b32_e32 v71, v131
	v_mov_b32_e32 v70, v131
	v_mov_b32_e32 v69, v131
	v_mov_b32_e32 v68, v131
	v_mov_b32_e32 v67, v131
	v_mov_b32_e32 v66, v131
	v_mov_b32_e32 v65, v131
	v_mov_b32_e32 v64, v131
	v_mov_b32_e32 v63, v131
	v_mov_b32_e32 v62, v131
	v_mov_b32_e32 v61, v131
	v_mov_b32_e32 v60, v131
	v_mov_b32_e32 v59, v131
	v_mov_b32_e32 v58, v131
	v_mov_b32_e32 v49, v131
	v_mov_b32_e32 v48, v131
	v_mov_b32_e32 v47, v131
	v_mov_b32_e32 v46, v131
	v_mov_b32_e32 v45, v131
	v_mov_b32_e32 v44, v131
	v_mov_b32_e32 v43, v131
	v_mov_b32_e32 v42, v131
	v_mov_b32_e32 v33, v131
	v_mov_b32_e32 v32, v131
	v_mov_b32_e32 v31, v131
	v_mov_b32_e32 v30, v131
	v_mov_b32_e32 v29, v131
	v_mov_b32_e32 v28, v131
	v_mov_b32_e32 v27, v131
	v_mov_b32_e32 v26, v131
	v_mov_b32_e32 v17, v131
	v_mov_b32_e32 v16, v131
	v_mov_b32_e32 v15, v131
	v_mov_b32_e32 v14, v131
	v_mov_b32_e32 v13, v131
	v_mov_b32_e32 v12, v131
	v_mov_b32_e32 v11, v131
	v_mov_b32_e32 v10, v131
	v_mov_b32_e32 v57, v131
	v_mov_b32_e32 v56, v131
	v_mov_b32_e32 v55, v131
	v_mov_b32_e32 v54, v131
	v_mov_b32_e32 v53, v131
	v_mov_b32_e32 v52, v131
	v_mov_b32_e32 v51, v131
	v_mov_b32_e32 v50, v131
	v_mov_b32_e32 v41, v131
	v_mov_b32_e32 v40, v131
	v_mov_b32_e32 v39, v131
	v_mov_b32_e32 v38, v131
	v_mov_b32_e32 v37, v131
	v_mov_b32_e32 v36, v131
	v_mov_b32_e32 v35, v131
	v_mov_b32_e32 v34, v131
	v_mov_b32_e32 v25, v131
	v_mov_b32_e32 v24, v131
	v_mov_b32_e32 v23, v131
	v_mov_b32_e32 v22, v131
	v_mov_b32_e32 v21, v131
	v_mov_b32_e32 v20, v131
	v_mov_b32_e32 v19, v131
	v_mov_b32_e32 v18, v131
	v_mov_b32_e32 v9, v131
	v_mov_b32_e32 v8, v131
	v_mov_b32_e32 v7, v131
	v_mov_b32_e32 v6, v131
	v_mov_b32_e32 v5, v131
	v_mov_b32_e32 v4, v131
	v_mov_b32_e32 v3, v131
	v_mov_b32_e32 v2, v131
	s_cbranch_vccnz .LBB0_877
	s_add_u32 s34, s34, 0x80
	s_addc_u32 s35, s35, 0
	s_add_u32 s4, s36, 0x100
	s_addc_u32 s16, s37, 0
	s_mov_b32 s17, 0

; template <class Epi, class Sched, bool ALIGN_EPI = false, bool SP2 = false>
; __device__ __forceinline__ void gemm_phase(PG8_LAS unsigned char* lds, const Gemm g, const Sched& S, const Epi& E) {
;     ...
;         if (!has_next) break;
; #pragma unroll
;         for (int a = 0; a < 2; ++a)
; #pragma unroll
;             for (int b = 0; b < 2; ++b)
; #pragma unroll
;                 for (int m = 0; m < 4; ++m)
; #pragma unroll
;                     for (int n = 0; n < 2; ++n) acc[a][b][m][n] = (f32x4){0.f, 0.f, 0.f, 0.f};
;         cur = nxt; cA = nA; cB = nB; ++ui;
.LBB0_965:
	v_mov_b32_e32 v131, 0
	s_andn2_b64 vcc, exec, s[52:53]
	v_mov_b32_e32 v130, v131
	v_mov_b32_e32 v129, v131
	v_mov_b32_e32 v128, v131
	v_mov_b32_e32 v127, v131
	v_mov_b32_e32 v126, v131
	v_mov_b32_e32 v125, v131
	v_mov_b32_e32 v124, v131
	v_mov_b32_e32 v115, v131
	v_mov_b32_e32 v114, v131
	v_mov_b32_e32 v113, v131
	v_mov_b32_e32 v112, v131
	v_mov_b32_e32 v111, v131
	v_mov_b32_e32 v110, v131
	v_mov_b32_e32 v109, v131
	v_mov_b32_e32 v108, v131
	v_mov_b32_e32 v97, v131
	v_mov_b32_e32 v96, v131
	v_mov_b32_e32 v95, v131
	v_mov_b32_e32 v94, v131
	v_mov_b32_e32 v93, v131
	v_mov_b32_e32 v92, v131
	v_mov_b32_e32 v91, v131
	v_mov_b32_e32 v90, v131
	v_mov_b32_e32 v81, v131
	v_mov_b32_e32 v80, v131
	v_mov_b32_e32 v79, v131
	v_mov_b32_e32 v78, v131
	v_mov_b32_e32 v77, v131
	v_mov_b32_e32 v76, v131
	v_mov_b32_e32 v75, v131
	v_mov_b32_e32 v74, v131
	v_mov_b32_e32 v123, v131
	v_mov_b32_e32 v122, v131
	v_mov_b32_e32 v121, v131
	v_mov_b32_e32 v120, v131
	v_mov_b32_e32 v119, v131
	v_mov_b32_e32 v118, v131
	v_mov_b32_e32 v117, v131
	v_mov_b32_e32 v116, v131
	v_mov_b32_e32 v107, v131
	v_mov_b32_e32 v106, v131
	v_mov_b32_e32 v105, v131
	v_mov_b32_e32 v104, v131
	v_mov_b32_e32 v103, v131
	v_mov_b32_e32 v102, v131
	v_mov_b32_e32 v101, v131
	v_mov_b32_e32 v100, v131
	v_mov_b32_e32 v89, v131
	v_mov_b32_e32 v88, v131
	v_mov_b32_e32 v87, v131
	v_mov_b32_e32 v86, v131
	v_mov_b32_e32 v85, v131
	v_mov_b32_e32 v84, v131
	v_mov_b32_e32 v83, v131
	v_mov_b32_e32 v82, v131
	v_mov_b32_e32 v73, v131
	v_mov_b32_e32 v72, v131
	v_mov_b32_e32 v71, v131
	v_mov_b32_e32 v70, v131
	v_mov_b32_e32 v69, v131
	v_mov_b32_e32 v68, v131
	v_mov_b32_e32 v67, v131
	v_mov_b32_e32 v66, v131
	v_mov_b32_e32 v65, v131
	v_mov_b32_e32 v64, v131
	v_mov_b32_e32 v63, v131
	v_mov_b32_e32 v62, v131
	v_mov_b32_e32 v61, v131
	v_mov_b32_e32 v60, v131
	v_mov_b32_e32 v59, v131
	v_mov_b32_e32 v58, v131
	v_mov_b32_e32 v49, v131
	v_mov_b32_e32 v48, v131
	v_mov_b32_e32 v47, v131
	v_mov_b32_e32 v46, v131
	v_mov_b32_e32 v45, v131
	v_mov_b32_e32 v44, v131
	v_mov_b32_e32 v43, v131
	v_mov_b32_e32 v42, v131
	v_mov_b32_e32 v33, v131
	v_mov_b32_e32 v32, v131
	v_mov_b32_e32 v31, v131
	v_mov_b32_e32 v30, v131
	v_mov_b32_e32 v29, v131
	v_mov_b32_e32 v28, v131
	v_mov_b32_e32 v27, v131
	v_mov_b32_e32 v26, v131
	v_mov_b32_e32 v17, v131
	v_mov_b32_e32 v16, v131
	v_mov_b32_e32 v15, v131
	v_mov_b32_e32 v14, v131
	v_mov_b32_e32 v13, v131
	v_mov_b32_e32 v12, v131
	v_mov_b32_e32 v11, v131
	v_mov_b32_e32 v10, v131
	v_mov_b32_e32 v57, v131
	v_mov_b32_e32 v56, v131
	v_mov_b32_e32 v55, v131
	v_mov_b32_e32 v54, v131
	v_mov_b32_e32 v53, v131
	v_mov_b32_e32 v52, v131
	v_mov_b32_e32 v51, v131
	v_mov_b32_e32 v50, v131
	v_mov_b32_e32 v41, v131
	v_mov_b32_e32 v40, v131
	v_mov_b32_e32 v39, v131
	v_mov_b32_e32 v38, v131
	v_mov_b32_e32 v37, v131
	v_mov_b32_e32 v36, v131
	v_mov_b32_e32 v35, v131
	v_mov_b32_e32 v34, v131
	v_mov_b32_e32 v25, v131
	v_mov_b32_e32 v24, v131
	v_mov_b32_e32 v23, v131
	v_mov_b32_e32 v22, v131
	v_mov_b32_e32 v21, v131
	v_mov_b32_e32 v20, v131
	v_mov_b32_e32 v19, v131
	v_mov_b32_e32 v18, v131
	v_mov_b32_e32 v9, v131
	v_mov_b32_e32 v8, v131
	v_mov_b32_e32 v7, v131
	v_mov_b32_e32 v6, v131
	v_mov_b32_e32 v5, v131
	v_mov_b32_e32 v4, v131
	v_mov_b32_e32 v3, v131
	v_mov_b32_e32 v2, v131
	s_cbranch_vccnz .LBB0_968
	s_add_u32 s34, s34, 0x80
	s_addc_u32 s35, s35, 0
	s_add_u32 s4, s36, 0x100
	s_addc_u32 s16, s37, 0
	s_mov_b32 s17, 0

; template <class Epi, class Sched, bool ALIGN_EPI = false, bool SP2 = false>
; __device__ __forceinline__ void gemm_phase(PG8_LAS unsigned char* lds, const Gemm g, const Sched& S, const Epi& E) {
;     ...
;         if (!has_next) break;
; #pragma unroll
;         for (int a = 0; a < 2; ++a)
; #pragma unroll
;             for (int b = 0; b < 2; ++b)
; #pragma unroll
;                 for (int m = 0; m < 4; ++m)
; #pragma unroll
;                     for (int n = 0; n < 2; ++n) acc[a][b][m][n] = (f32x4){0.f, 0.f, 0.f, 0.f};
;         cur = nxt; cA = nA; cB = nB; ++ui;
.LBB0_1050:
	v_mov_b32_e32 v131, 0
	s_andn2_b64 vcc, exec, s[50:51]
	v_mov_b32_e32 v130, v131
	v_mov_b32_e32 v129, v131
	v_mov_b32_e32 v128, v131
	v_mov_b32_e32 v127, v131
	v_mov_b32_e32 v126, v131
	v_mov_b32_e32 v125, v131
	v_mov_b32_e32 v124, v131
	v_mov_b32_e32 v123, v131
	v_mov_b32_e32 v122, v131
	v_mov_b32_e32 v121, v131
	v_mov_b32_e32 v120, v131
	v_mov_b32_e32 v119, v131
	v_mov_b32_e32 v118, v131
	v_mov_b32_e32 v117, v131
	v_mov_b32_e32 v116, v131
	v_mov_b32_e32 v115, v131
	v_mov_b32_e32 v114, v131
	v_mov_b32_e32 v113, v131
	v_mov_b32_e32 v112, v131
	v_mov_b32_e32 v111, v131
	v_mov_b32_e32 v110, v131
	v_mov_b32_e32 v109, v131
	v_mov_b32_e32 v108, v131
	v_mov_b32_e32 v107, v131
	v_mov_b32_e32 v106, v131
	v_mov_b32_e32 v105, v131
	v_mov_b32_e32 v104, v131
	v_mov_b32_e32 v103, v131
	v_mov_b32_e32 v102, v131
	v_mov_b32_e32 v101, v131
	v_mov_b32_e32 v100, v131
	v_mov_b32_e32 v65, v131
	v_mov_b32_e32 v64, v131
	v_mov_b32_e32 v63, v131
	v_mov_b32_e32 v62, v131
	v_mov_b32_e32 v61, v131
	v_mov_b32_e32 v60, v131
	v_mov_b32_e32 v59, v131
	v_mov_b32_e32 v58, v131
	v_mov_b32_e32 v57, v131
	v_mov_b32_e32 v56, v131
	v_mov_b32_e32 v55, v131
	v_mov_b32_e32 v54, v131
	v_mov_b32_e32 v53, v131
	v_mov_b32_e32 v52, v131
	v_mov_b32_e32 v51, v131
	v_mov_b32_e32 v50, v131
	v_mov_b32_e32 v49, v131
	v_mov_b32_e32 v48, v131
	v_mov_b32_e32 v47, v131
	v_mov_b32_e32 v46, v131
	v_mov_b32_e32 v45, v131
	v_mov_b32_e32 v44, v131
	v_mov_b32_e32 v43, v131
	v_mov_b32_e32 v42, v131
	v_mov_b32_e32 v41, v131
	v_mov_b32_e32 v40, v131
	v_mov_b32_e32 v39, v131
	v_mov_b32_e32 v38, v131
	v_mov_b32_e32 v37, v131
	v_mov_b32_e32 v36, v131
	v_mov_b32_e32 v35, v131
	v_mov_b32_e32 v34, v131
	v_mov_b32_e32 v97, v131
	v_mov_b32_e32 v96, v131
	v_mov_b32_e32 v95, v131
	v_mov_b32_e32 v94, v131
	v_mov_b32_e32 v93, v131
	v_mov_b32_e32 v92, v131
	v_mov_b32_e32 v91, v131
	v_mov_b32_e32 v90, v131
	v_mov_b32_e32 v89, v131
	v_mov_b32_e32 v88, v131
	v_mov_b32_e32 v87, v131
	v_mov_b32_e32 v86, v131
	v_mov_b32_e32 v85, v131
	v_mov_b32_e32 v84, v131
	v_mov_b32_e32 v83, v131
	v_mov_b32_e32 v82, v131
	v_mov_b32_e32 v81, v131
	v_mov_b32_e32 v80, v131
	v_mov_b32_e32 v79, v131
	v_mov_b32_e32 v78, v131
	v_mov_b32_e32 v77, v131
	v_mov_b32_e32 v76, v131
	v_mov_b32_e32 v75, v131
	v_mov_b32_e32 v74, v131
	v_mov_b32_e32 v73, v131
	v_mov_b32_e32 v72, v131
	v_mov_b32_e32 v71, v131
	v_mov_b32_e32 v70, v131
	v_mov_b32_e32 v69, v131
	v_mov_b32_e32 v68, v131
	v_mov_b32_e32 v67, v131
	v_mov_b32_e32 v66, v131
	v_mov_b32_e32 v33, v131
	v_mov_b32_e32 v32, v131
	v_mov_b32_e32 v31, v131
	v_mov_b32_e32 v30, v131
	v_mov_b32_e32 v29, v131
	v_mov_b32_e32 v28, v131
	v_mov_b32_e32 v27, v131
	v_mov_b32_e32 v26, v131
	v_mov_b32_e32 v25, v131
	v_mov_b32_e32 v24, v131
	v_mov_b32_e32 v23, v131
	v_mov_b32_e32 v22, v131
	v_mov_b32_e32 v21, v131
	v_mov_b32_e32 v20, v131
	v_mov_b32_e32 v19, v131
	v_mov_b32_e32 v18, v131
	v_mov_b32_e32 v17, v131
	v_mov_b32_e32 v16, v131
	v_mov_b32_e32 v15, v131
	v_mov_b32_e32 v14, v131
	v_mov_b32_e32 v13, v131
	v_mov_b32_e32 v12, v131
	v_mov_b32_e32 v11, v131
	v_mov_b32_e32 v10, v131
	v_mov_b32_e32 v9, v131
	v_mov_b32_e32 v8, v131
	v_mov_b32_e32 v7, v131
	v_mov_b32_e32 v6, v131
	v_mov_b32_e32 v5, v131
	v_mov_b32_e32 v4, v131
	v_mov_b32_e32 v3, v131
	v_mov_b32_e32 v2, v131
	s_cbranch_vccnz .LBB0_1053
	s_add_u32 s2, s36, 0x80
	s_addc_u32 s3, s37, 0
	s_add_u32 s4, s34, 0x100
	s_addc_u32 s16, s35, 0
	s_mov_b32 s17, 0

; template <class Epi, class Sched, bool ALIGN_EPI = false, bool SP2 = false>
; __device__ __forceinline__ void gemm_phase(PG8_LAS unsigned char* lds, const Gemm g, const Sched& S, const Epi& E) {
;     ...
;         if (!has_next) break;
; #pragma unroll
;         for (int a = 0; a < 2; ++a)
; #pragma unroll
;             for (int b = 0; b < 2; ++b)
; #pragma unroll
;                 for (int m = 0; m < 4; ++m)
; #pragma unroll
;                     for (int n = 0; n < 2; ++n) acc[a][b][m][n] = (f32x4){0.f, 0.f, 0.f, 0.f};
;         cur = nxt; cA = nA; cB = nB; ++ui;
.LBB0_1125:
	v_mov_b32_e32 v127, 0
	s_andn2_b64 vcc, exec, s[52:53]
	v_mov_b32_e32 v126, v127
	v_mov_b32_e32 v125, v127
	v_mov_b32_e32 v124, v127
	v_mov_b32_e32 v131, v127
	v_mov_b32_e32 v130, v127
	v_mov_b32_e32 v129, v127
	v_mov_b32_e32 v128, v127
	v_mov_b32_e32 v115, v127
	v_mov_b32_e32 v114, v127
	v_mov_b32_e32 v113, v127
	v_mov_b32_e32 v112, v127
	v_mov_b32_e32 v111, v127
	v_mov_b32_e32 v110, v127
	v_mov_b32_e32 v109, v127
	v_mov_b32_e32 v108, v127
	v_mov_b32_e32 v97, v127
	v_mov_b32_e32 v96, v127
	v_mov_b32_e32 v95, v127
	v_mov_b32_e32 v94, v127
	v_mov_b32_e32 v93, v127
	v_mov_b32_e32 v92, v127
	v_mov_b32_e32 v91, v127
	v_mov_b32_e32 v90, v127
	v_mov_b32_e32 v81, v127
	v_mov_b32_e32 v80, v127
	v_mov_b32_e32 v79, v127
	v_mov_b32_e32 v78, v127
	v_mov_b32_e32 v77, v127
	v_mov_b32_e32 v76, v127
	v_mov_b32_e32 v75, v127
	v_mov_b32_e32 v74, v127
	v_mov_b32_e32 v123, v127
	v_mov_b32_e32 v122, v127
	v_mov_b32_e32 v121, v127
	v_mov_b32_e32 v120, v127
	v_mov_b32_e32 v119, v127
	v_mov_b32_e32 v118, v127
	v_mov_b32_e32 v117, v127
	v_mov_b32_e32 v116, v127
	v_mov_b32_e32 v107, v127
	v_mov_b32_e32 v106, v127
	v_mov_b32_e32 v105, v127
	v_mov_b32_e32 v104, v127
	v_mov_b32_e32 v103, v127
	v_mov_b32_e32 v102, v127
	v_mov_b32_e32 v101, v127
	v_mov_b32_e32 v100, v127
	v_mov_b32_e32 v89, v127
	v_mov_b32_e32 v88, v127
	v_mov_b32_e32 v87, v127
	v_mov_b32_e32 v86, v127
	v_mov_b32_e32 v85, v127
	v_mov_b32_e32 v84, v127
	v_mov_b32_e32 v83, v127
	v_mov_b32_e32 v82, v127
	v_mov_b32_e32 v73, v127
	v_mov_b32_e32 v72, v127
	v_mov_b32_e32 v71, v127
	v_mov_b32_e32 v70, v127
	v_mov_b32_e32 v69, v127
	v_mov_b32_e32 v68, v127
	v_mov_b32_e32 v67, v127
	v_mov_b32_e32 v66, v127
	v_mov_b32_e32 v65, v127
	v_mov_b32_e32 v64, v127
	v_mov_b32_e32 v63, v127
	v_mov_b32_e32 v62, v127
	v_mov_b32_e32 v61, v127
	v_mov_b32_e32 v60, v127
	v_mov_b32_e32 v59, v127
	v_mov_b32_e32 v58, v127
	v_mov_b32_e32 v49, v127
	v_mov_b32_e32 v48, v127
	v_mov_b32_e32 v47, v127
	v_mov_b32_e32 v46, v127
	v_mov_b32_e32 v45, v127
	v_mov_b32_e32 v44, v127
	v_mov_b32_e32 v43, v127
	v_mov_b32_e32 v42, v127
	v_mov_b32_e32 v33, v127
	v_mov_b32_e32 v32, v127
	v_mov_b32_e32 v31, v127
	v_mov_b32_e32 v30, v127
	v_mov_b32_e32 v29, v127
	v_mov_b32_e32 v28, v127
	v_mov_b32_e32 v27, v127
	v_mov_b32_e32 v26, v127
	v_mov_b32_e32 v17, v127
	v_mov_b32_e32 v16, v127
	v_mov_b32_e32 v15, v127
	v_mov_b32_e32 v14, v127
	v_mov_b32_e32 v13, v127
	v_mov_b32_e32 v12, v127
	v_mov_b32_e32 v11, v127
	v_mov_b32_e32 v10, v127
	v_mov_b32_e32 v57, v127
	v_mov_b32_e32 v56, v127
	v_mov_b32_e32 v55, v127
	v_mov_b32_e32 v54, v127
	v_mov_b32_e32 v53, v127
	v_mov_b32_e32 v52, v127
	v_mov_b32_e32 v51, v127
	v_mov_b32_e32 v50, v127
	v_mov_b32_e32 v41, v127
	v_mov_b32_e32 v40, v127
	v_mov_b32_e32 v39, v127
	v_mov_b32_e32 v38, v127
	v_mov_b32_e32 v37, v127
	v_mov_b32_e32 v36, v127
	v_mov_b32_e32 v35, v127
	v_mov_b32_e32 v34, v127
	v_mov_b32_e32 v25, v127
	v_mov_b32_e32 v24, v127
	v_mov_b32_e32 v23, v127
	v_mov_b32_e32 v22, v127
	v_mov_b32_e32 v21, v127
	v_mov_b32_e32 v20, v127
	v_mov_b32_e32 v19, v127
	v_mov_b32_e32 v18, v127
	v_mov_b32_e32 v9, v127
	v_mov_b32_e32 v8, v127
	v_mov_b32_e32 v7, v127
	v_mov_b32_e32 v6, v127
	v_mov_b32_e32 v5, v127
	v_mov_b32_e32 v4, v127
	v_mov_b32_e32 v3, v127
	v_mov_b32_e32 v2, v127
	s_cbranch_vccnz .LBB0_1128
	s_add_u32 s2, s36, 0x80
	s_addc_u32 s3, s37, 0
	s_add_u32 s4, s34, 0x100
	s_addc_u32 s16, s35, 0
	s_mov_b32 s17, 0

; template <class Epi, class Sched, bool ALIGN_EPI = false, bool SP2 = false>
; __device__ __forceinline__ void gemm_phase(PG8_LAS unsigned char* lds, const Gemm g, const Sched& S, const Epi& E) {
;     ...
;         if (!has_next) break;
; #pragma unroll
;         for (int a = 0; a < 2; ++a)
; #pragma unroll
;             for (int b = 0; b < 2; ++b)
; #pragma unroll
;                 for (int m = 0; m < 4; ++m)
; #pragma unroll
;                     for (int n = 0; n < 2; ++n) acc[a][b][m][n] = (f32x4){0.f, 0.f, 0.f, 0.f};
;         cur = nxt; cA = nA; cB = nB; ++ui;
.LBB0_1207:
	v_mov_b32_e32 v131, 0
	s_andn2_b64 vcc, exec, s[46:47]
	v_mov_b32_e32 v130, v131
	v_mov_b32_e32 v129, v131
	v_mov_b32_e32 v128, v131
	v_mov_b32_e32 v127, v131
	v_mov_b32_e32 v126, v131
	v_mov_b32_e32 v125, v131
	v_mov_b32_e32 v124, v131
	v_mov_b32_e32 v123, v131
	v_mov_b32_e32 v122, v131
	v_mov_b32_e32 v121, v131
	v_mov_b32_e32 v120, v131
	v_mov_b32_e32 v119, v131
	v_mov_b32_e32 v118, v131
	v_mov_b32_e32 v117, v131
	v_mov_b32_e32 v116, v131
	v_mov_b32_e32 v115, v131
	v_mov_b32_e32 v114, v131
	v_mov_b32_e32 v113, v131
	v_mov_b32_e32 v112, v131
	v_mov_b32_e32 v111, v131
	v_mov_b32_e32 v110, v131
	v_mov_b32_e32 v109, v131
	v_mov_b32_e32 v108, v131
	v_mov_b32_e32 v107, v131
	v_mov_b32_e32 v106, v131
	v_mov_b32_e32 v105, v131
	v_mov_b32_e32 v104, v131
	v_mov_b32_e32 v103, v131
	v_mov_b32_e32 v102, v131
	v_mov_b32_e32 v101, v131
	v_mov_b32_e32 v100, v131
	v_mov_b32_e32 v65, v131
	v_mov_b32_e32 v64, v131
	v_mov_b32_e32 v63, v131
	v_mov_b32_e32 v62, v131
	v_mov_b32_e32 v61, v131
	v_mov_b32_e32 v60, v131
	v_mov_b32_e32 v59, v131
	v_mov_b32_e32 v58, v131
	v_mov_b32_e32 v57, v131
	v_mov_b32_e32 v56, v131
	v_mov_b32_e32 v55, v131
	v_mov_b32_e32 v54, v131
	v_mov_b32_e32 v53, v131
	v_mov_b32_e32 v52, v131
	v_mov_b32_e32 v51, v131
	v_mov_b32_e32 v50, v131
	v_mov_b32_e32 v49, v131
	v_mov_b32_e32 v48, v131
	v_mov_b32_e32 v47, v131
	v_mov_b32_e32 v46, v131
	v_mov_b32_e32 v45, v131
	v_mov_b32_e32 v44, v131
	v_mov_b32_e32 v43, v131
	v_mov_b32_e32 v42, v131
	v_mov_b32_e32 v41, v131
	v_mov_b32_e32 v40, v131
	v_mov_b32_e32 v39, v131
	v_mov_b32_e32 v38, v131
	v_mov_b32_e32 v37, v131
	v_mov_b32_e32 v36, v131
	v_mov_b32_e32 v35, v131
	v_mov_b32_e32 v34, v131
	v_mov_b32_e32 v97, v131
	v_mov_b32_e32 v96, v131
	v_mov_b32_e32 v95, v131
	v_mov_b32_e32 v94, v131
	v_mov_b32_e32 v93, v131
	v_mov_b32_e32 v92, v131
	v_mov_b32_e32 v91, v131
	v_mov_b32_e32 v90, v131
	v_mov_b32_e32 v89, v131
	v_mov_b32_e32 v88, v131
	v_mov_b32_e32 v87, v131
	v_mov_b32_e32 v86, v131
	v_mov_b32_e32 v85, v131
	v_mov_b32_e32 v84, v131
	v_mov_b32_e32 v83, v131
	v_mov_b32_e32 v82, v131
	v_mov_b32_e32 v81, v131
	v_mov_b32_e32 v80, v131
	v_mov_b32_e32 v79, v131
	v_mov_b32_e32 v78, v131
	v_mov_b32_e32 v77, v131
	v_mov_b32_e32 v76, v131
	v_mov_b32_e32 v75, v131
	v_mov_b32_e32 v74, v131
	v_mov_b32_e32 v73, v131
	v_mov_b32_e32 v72, v131
	v_mov_b32_e32 v71, v131
	v_mov_b32_e32 v70, v131
	v_mov_b32_e32 v69, v131
	v_mov_b32_e32 v68, v131
	v_mov_b32_e32 v67, v131
	v_mov_b32_e32 v66, v131
	v_mov_b32_e32 v33, v131
	v_mov_b32_e32 v32, v131
	v_mov_b32_e32 v31, v131
	v_mov_b32_e32 v30, v131
	v_mov_b32_e32 v29, v131
	v_mov_b32_e32 v28, v131
	v_mov_b32_e32 v27, v131
	v_mov_b32_e32 v26, v131
	v_mov_b32_e32 v25, v131
	v_mov_b32_e32 v24, v131
	v_mov_b32_e32 v23, v131
	v_mov_b32_e32 v22, v131
	v_mov_b32_e32 v21, v131
	v_mov_b32_e32 v20, v131
	v_mov_b32_e32 v19, v131
	v_mov_b32_e32 v18, v131
	v_mov_b32_e32 v17, v131
	v_mov_b32_e32 v16, v131
	v_mov_b32_e32 v15, v131
	v_mov_b32_e32 v14, v131
	v_mov_b32_e32 v13, v131
	v_mov_b32_e32 v12, v131
	v_mov_b32_e32 v11, v131
	v_mov_b32_e32 v10, v131
	v_mov_b32_e32 v9, v131
	v_mov_b32_e32 v8, v131
	v_mov_b32_e32 v7, v131
	v_mov_b32_e32 v6, v131
	v_mov_b32_e32 v5, v131
	v_mov_b32_e32 v4, v131
	v_mov_b32_e32 v3, v131
	v_mov_b32_e32 v2, v131
	s_cbranch_vccnz .LBB0_1210
	s_add_u32 s2, s36, 0x80
	s_addc_u32 s3, s37, 0
	s_add_u32 s4, s34, 0x100
	s_addc_u32 s16, s35, 0
	s_mov_b32 s17, 0

; template <class Epi, class Sched, bool ALIGN_EPI = false, bool SP2 = false>
; __device__ __forceinline__ void gemm_phase(PG8_LAS unsigned char* lds, const Gemm g, const Sched& S, const Epi& E) {
;     ...
;         if (!has_next) break;
; #pragma unroll
;         for (int a = 0; a < 2; ++a)
; #pragma unroll
;             for (int b = 0; b < 2; ++b)
; #pragma unroll
;                 for (int m = 0; m < 4; ++m)
; #pragma unroll
;                     for (int n = 0; n < 2; ++n) acc[a][b][m][n] = (f32x4){0.f, 0.f, 0.f, 0.f};
;         cur = nxt; cA = nA; cB = nB; ++ui;
.LBB0_1481:
	v_mov_b32_e32 v127, 0
	s_andn2_b64 vcc, exec, s[46:47]
	v_mov_b32_e32 v126, v127
	v_mov_b32_e32 v125, v127
	v_mov_b32_e32 v124, v127
	v_mov_b32_e32 v123, v127
	v_mov_b32_e32 v122, v127
	v_mov_b32_e32 v121, v127
	v_mov_b32_e32 v120, v127
	v_mov_b32_e32 v115, v127
	v_mov_b32_e32 v114, v127
	v_mov_b32_e32 v113, v127
	v_mov_b32_e32 v112, v127
	v_mov_b32_e32 v107, v127
	v_mov_b32_e32 v106, v127
	v_mov_b32_e32 v105, v127
	v_mov_b32_e32 v104, v127
	v_mov_b32_e32 v97, v127
	v_mov_b32_e32 v96, v127
	v_mov_b32_e32 v95, v127
	v_mov_b32_e32 v94, v127
	v_mov_b32_e32 v89, v127
	v_mov_b32_e32 v88, v127
	v_mov_b32_e32 v87, v127
	v_mov_b32_e32 v86, v127
	v_mov_b32_e32 v81, v127
	v_mov_b32_e32 v80, v127
	v_mov_b32_e32 v79, v127
	v_mov_b32_e32 v78, v127
	v_mov_b32_e32 v73, v127
	v_mov_b32_e32 v72, v127
	v_mov_b32_e32 v71, v127
	v_mov_b32_e32 v70, v127
	v_mov_b32_e32 v131, v127
	v_mov_b32_e32 v130, v127
	v_mov_b32_e32 v129, v127
	v_mov_b32_e32 v128, v127
	v_mov_b32_e32 v119, v127
	v_mov_b32_e32 v118, v127
	v_mov_b32_e32 v117, v127
	v_mov_b32_e32 v116, v127
	v_mov_b32_e32 v111, v127
	v_mov_b32_e32 v110, v127
	v_mov_b32_e32 v109, v127
	v_mov_b32_e32 v108, v127
	v_mov_b32_e32 v103, v127
	v_mov_b32_e32 v102, v127
	v_mov_b32_e32 v101, v127
	v_mov_b32_e32 v100, v127
	v_mov_b32_e32 v93, v127
	v_mov_b32_e32 v92, v127
	v_mov_b32_e32 v91, v127
	v_mov_b32_e32 v90, v127
	v_mov_b32_e32 v85, v127
	v_mov_b32_e32 v84, v127
	v_mov_b32_e32 v83, v127
	v_mov_b32_e32 v82, v127
	v_mov_b32_e32 v77, v127
	v_mov_b32_e32 v76, v127
	v_mov_b32_e32 v75, v127
	v_mov_b32_e32 v74, v127
	v_mov_b32_e32 v69, v127
	v_mov_b32_e32 v68, v127
	v_mov_b32_e32 v67, v127
	v_mov_b32_e32 v66, v127
	v_mov_b32_e32 v65, v127
	v_mov_b32_e32 v64, v127
	v_mov_b32_e32 v63, v127
	v_mov_b32_e32 v62, v127
	v_mov_b32_e32 v57, v127
	v_mov_b32_e32 v56, v127
	v_mov_b32_e32 v55, v127
	v_mov_b32_e32 v54, v127
	v_mov_b32_e32 v49, v127
	v_mov_b32_e32 v48, v127
	v_mov_b32_e32 v47, v127
	v_mov_b32_e32 v46, v127
	v_mov_b32_e32 v41, v127
	v_mov_b32_e32 v40, v127
	v_mov_b32_e32 v39, v127
	v_mov_b32_e32 v38, v127
	v_mov_b32_e32 v33, v127
	v_mov_b32_e32 v32, v127
	v_mov_b32_e32 v31, v127
	v_mov_b32_e32 v30, v127
	v_mov_b32_e32 v25, v127
	v_mov_b32_e32 v24, v127
	v_mov_b32_e32 v23, v127
	v_mov_b32_e32 v22, v127
	v_mov_b32_e32 v17, v127
	v_mov_b32_e32 v16, v127
	v_mov_b32_e32 v15, v127
	v_mov_b32_e32 v14, v127
	v_mov_b32_e32 v9, v127
	v_mov_b32_e32 v8, v127
	v_mov_b32_e32 v7, v127
	v_mov_b32_e32 v6, v127
	v_mov_b32_e32 v61, v127
	v_mov_b32_e32 v60, v127
	v_mov_b32_e32 v59, v127
	v_mov_b32_e32 v58, v127
	v_mov_b32_e32 v53, v127
	v_mov_b32_e32 v52, v127
	v_mov_b32_e32 v51, v127
	v_mov_b32_e32 v50, v127
	v_mov_b32_e32 v45, v127
	v_mov_b32_e32 v44, v127
	v_mov_b32_e32 v43, v127
	v_mov_b32_e32 v42, v127
	v_mov_b32_e32 v37, v127
	v_mov_b32_e32 v36, v127
	v_mov_b32_e32 v35, v127
	v_mov_b32_e32 v34, v127
	v_mov_b32_e32 v29, v127
	v_mov_b32_e32 v28, v127
	v_mov_b32_e32 v27, v127
	v_mov_b32_e32 v26, v127
	v_mov_b32_e32 v21, v127
	v_mov_b32_e32 v20, v127
	v_mov_b32_e32 v19, v127
	v_mov_b32_e32 v18, v127
	v_mov_b32_e32 v13, v127
	v_mov_b32_e32 v12, v127
	v_mov_b32_e32 v11, v127
	v_mov_b32_e32 v10, v127
	v_mov_b32_e32 v5, v127
	v_mov_b32_e32 v4, v127
	v_mov_b32_e32 v3, v127
	v_mov_b32_e32 v2, v127
	s_cbranch_vccnz .LBB0_1484
	s_add_u32 s2, s36, 0x80
	s_addc_u32 s3, s37, 0
	s_add_u32 s4, s34, 0x100
	s_addc_u32 s16, s35, 0
	s_mov_b32 s17, 0

; template <class Epi, class Sched, bool ALIGN_EPI = false, bool SP2 = false>
; __device__ __forceinline__ void gemm_phase(PG8_LAS unsigned char* lds, const Gemm g, const Sched& S, const Epi& E) {
;     ...
;         if (!has_next) break;
; #pragma unroll
;         for (int a = 0; a < 2; ++a)
; #pragma unroll
;             for (int b = 0; b < 2; ++b)
; #pragma unroll
;                 for (int m = 0; m < 4; ++m)
; #pragma unroll
;                     for (int n = 0; n < 2; ++n) acc[a][b][m][n] = (f32x4){0.f, 0.f, 0.f, 0.f};
;         cur = nxt; cA = nA; cB = nB; ++ui;
.LBB0_1760:
	v_mov_b32_e32 v131, 0
	s_andn2_b64 vcc, exec, s[48:49]
	v_mov_b32_e32 v130, v131
	v_mov_b32_e32 v129, v131
	v_mov_b32_e32 v128, v131
	v_mov_b32_e32 v127, v131
	v_mov_b32_e32 v126, v131
	v_mov_b32_e32 v125, v131
	v_mov_b32_e32 v124, v131
	v_mov_b32_e32 v115, v131
	v_mov_b32_e32 v114, v131
	v_mov_b32_e32 v113, v131
	v_mov_b32_e32 v112, v131
	v_mov_b32_e32 v111, v131
	v_mov_b32_e32 v110, v131
	v_mov_b32_e32 v109, v131
	v_mov_b32_e32 v108, v131
	v_mov_b32_e32 v97, v131
	v_mov_b32_e32 v96, v131
	v_mov_b32_e32 v95, v131
	v_mov_b32_e32 v94, v131
	v_mov_b32_e32 v93, v131
	v_mov_b32_e32 v92, v131
	v_mov_b32_e32 v91, v131
	v_mov_b32_e32 v90, v131
	v_mov_b32_e32 v81, v131
	v_mov_b32_e32 v80, v131
	v_mov_b32_e32 v79, v131
	v_mov_b32_e32 v78, v131
	v_mov_b32_e32 v77, v131
	v_mov_b32_e32 v76, v131
	v_mov_b32_e32 v75, v131
	v_mov_b32_e32 v74, v131
	v_mov_b32_e32 v123, v131
	v_mov_b32_e32 v122, v131
	v_mov_b32_e32 v121, v131
	v_mov_b32_e32 v120, v131
	v_mov_b32_e32 v119, v131
	v_mov_b32_e32 v118, v131
	v_mov_b32_e32 v117, v131
	v_mov_b32_e32 v116, v131
	v_mov_b32_e32 v107, v131
	v_mov_b32_e32 v106, v131
	v_mov_b32_e32 v105, v131
	v_mov_b32_e32 v104, v131
	v_mov_b32_e32 v103, v131
	v_mov_b32_e32 v102, v131
	v_mov_b32_e32 v101, v131
	v_mov_b32_e32 v100, v131
	v_mov_b32_e32 v89, v131
	v_mov_b32_e32 v88, v131
	v_mov_b32_e32 v87, v131
	v_mov_b32_e32 v86, v131
	v_mov_b32_e32 v85, v131
	v_mov_b32_e32 v84, v131
	v_mov_b32_e32 v83, v131
	v_mov_b32_e32 v82, v131
	v_mov_b32_e32 v73, v131
	v_mov_b32_e32 v72, v131
	v_mov_b32_e32 v71, v131
	v_mov_b32_e32 v70, v131
	v_mov_b32_e32 v69, v131
	v_mov_b32_e32 v68, v131
	v_mov_b32_e32 v67, v131
	v_mov_b32_e32 v66, v131
	v_mov_b32_e32 v65, v131
	v_mov_b32_e32 v64, v131
	v_mov_b32_e32 v63, v131
	v_mov_b32_e32 v62, v131
	v_mov_b32_e32 v61, v131
	v_mov_b32_e32 v60, v131
	v_mov_b32_e32 v59, v131
	v_mov_b32_e32 v58, v131
	v_mov_b32_e32 v49, v131
	v_mov_b32_e32 v48, v131
	v_mov_b32_e32 v47, v131
	v_mov_b32_e32 v46, v131
	v_mov_b32_e32 v45, v131
	v_mov_b32_e32 v44, v131
	v_mov_b32_e32 v43, v131
	v_mov_b32_e32 v42, v131
	v_mov_b32_e32 v33, v131
	v_mov_b32_e32 v32, v131
	v_mov_b32_e32 v31, v131
	v_mov_b32_e32 v30, v131
	v_mov_b32_e32 v29, v131
	v_mov_b32_e32 v28, v131
	v_mov_b32_e32 v27, v131
	v_mov_b32_e32 v26, v131
	v_mov_b32_e32 v17, v131
	v_mov_b32_e32 v16, v131
	v_mov_b32_e32 v15, v131
	v_mov_b32_e32 v14, v131
	v_mov_b32_e32 v13, v131
	v_mov_b32_e32 v12, v131
	v_mov_b32_e32 v11, v131
	v_mov_b32_e32 v10, v131
	v_mov_b32_e32 v57, v131
	v_mov_b32_e32 v56, v131
	v_mov_b32_e32 v55, v131
	v_mov_b32_e32 v54, v131
	v_mov_b32_e32 v53, v131
	v_mov_b32_e32 v52, v131
	v_mov_b32_e32 v51, v131
	v_mov_b32_e32 v50, v131
	v_mov_b32_e32 v41, v131
	v_mov_b32_e32 v40, v131
	v_mov_b32_e32 v39, v131
	v_mov_b32_e32 v38, v131
	v_mov_b32_e32 v37, v131
	v_mov_b32_e32 v36, v131
	v_mov_b32_e32 v35, v131
	v_mov_b32_e32 v34, v131
	v_mov_b32_e32 v25, v131
	v_mov_b32_e32 v24, v131
	v_mov_b32_e32 v23, v131
	v_mov_b32_e32 v22, v131
	v_mov_b32_e32 v21, v131
	v_mov_b32_e32 v20, v131
	v_mov_b32_e32 v19, v131
	v_mov_b32_e32 v18, v131
	v_mov_b32_e32 v9, v131
	v_mov_b32_e32 v8, v131
	v_mov_b32_e32 v7, v131
	v_mov_b32_e32 v6, v131
	v_mov_b32_e32 v5, v131
	v_mov_b32_e32 v4, v131
	v_mov_b32_e32 v3, v131
	v_mov_b32_e32 v2, v131
	s_cbranch_vccnz .LBB0_1763
	s_add_u32 s34, s34, 0x80
	s_addc_u32 s35, s35, 0
	s_add_u32 s4, s36, 0x100
	s_addc_u32 s16, s37, 0
	s_mov_b32 s17, 0

; template <class Epi, class Sched, bool ALIGN_EPI = false, bool SP2 = false>
; __device__ __forceinline__ void gemm_phase(PG8_LAS unsigned char* lds, const Gemm g, const Sched& S, const Epi& E) {
;     ...
;         if (!has_next) break;
; #pragma unroll
;         for (int a = 0; a < 2; ++a)
; #pragma unroll
;             for (int b = 0; b < 2; ++b)
; #pragma unroll
;                 for (int m = 0; m < 4; ++m)
; #pragma unroll
;                     for (int n = 0; n < 2; ++n) acc[a][b][m][n] = (f32x4){0.f, 0.f, 0.f, 0.f};
;         cur = nxt; cA = nA; cB = nB; ++ui;
.LBB0_1851:
	v_mov_b32_e32 v127, 0
	s_andn2_b64 vcc, exec, s[54:55]
	v_mov_b32_e32 v126, v127
	v_mov_b32_e32 v125, v127
	v_mov_b32_e32 v124, v127
	v_mov_b32_e32 v131, v127
	v_mov_b32_e32 v130, v127
	v_mov_b32_e32 v129, v127
	v_mov_b32_e32 v128, v127
	v_mov_b32_e32 v115, v127
	v_mov_b32_e32 v114, v127
	v_mov_b32_e32 v113, v127
	v_mov_b32_e32 v112, v127
	v_mov_b32_e32 v111, v127
	v_mov_b32_e32 v110, v127
	v_mov_b32_e32 v109, v127
	v_mov_b32_e32 v108, v127
	v_mov_b32_e32 v97, v127
	v_mov_b32_e32 v96, v127
	v_mov_b32_e32 v95, v127
	v_mov_b32_e32 v94, v127
	v_mov_b32_e32 v93, v127
	v_mov_b32_e32 v92, v127
	v_mov_b32_e32 v91, v127
	v_mov_b32_e32 v90, v127
	v_mov_b32_e32 v81, v127
	v_mov_b32_e32 v80, v127
	v_mov_b32_e32 v79, v127
	v_mov_b32_e32 v78, v127
	v_mov_b32_e32 v77, v127
	v_mov_b32_e32 v76, v127
	v_mov_b32_e32 v75, v127
	v_mov_b32_e32 v74, v127
	v_mov_b32_e32 v123, v127
	v_mov_b32_e32 v122, v127
	v_mov_b32_e32 v121, v127
	v_mov_b32_e32 v120, v127
	v_mov_b32_e32 v119, v127
	v_mov_b32_e32 v118, v127
	v_mov_b32_e32 v117, v127
	v_mov_b32_e32 v116, v127
	v_mov_b32_e32 v107, v127
	v_mov_b32_e32 v106, v127
	v_mov_b32_e32 v105, v127
	v_mov_b32_e32 v104, v127
	v_mov_b32_e32 v103, v127
	v_mov_b32_e32 v102, v127
	v_mov_b32_e32 v101, v127
	v_mov_b32_e32 v100, v127
	v_mov_b32_e32 v89, v127
	v_mov_b32_e32 v88, v127
	v_mov_b32_e32 v87, v127
	v_mov_b32_e32 v86, v127
	v_mov_b32_e32 v85, v127
	v_mov_b32_e32 v84, v127
	v_mov_b32_e32 v83, v127
	v_mov_b32_e32 v82, v127
	v_mov_b32_e32 v73, v127
	v_mov_b32_e32 v72, v127
	v_mov_b32_e32 v71, v127
	v_mov_b32_e32 v70, v127
	v_mov_b32_e32 v69, v127
	v_mov_b32_e32 v68, v127
	v_mov_b32_e32 v67, v127
	v_mov_b32_e32 v66, v127
	v_mov_b32_e32 v65, v127
	v_mov_b32_e32 v64, v127
	v_mov_b32_e32 v63, v127
	v_mov_b32_e32 v62, v127
	v_mov_b32_e32 v61, v127
	v_mov_b32_e32 v60, v127
	v_mov_b32_e32 v59, v127
	v_mov_b32_e32 v58, v127
	v_mov_b32_e32 v49, v127
	v_mov_b32_e32 v48, v127
	v_mov_b32_e32 v47, v127
	v_mov_b32_e32 v46, v127
	v_mov_b32_e32 v45, v127
	v_mov_b32_e32 v44, v127
	v_mov_b32_e32 v43, v127
	v_mov_b32_e32 v42, v127
	v_mov_b32_e32 v33, v127
	v_mov_b32_e32 v32, v127
	v_mov_b32_e32 v31, v127
	v_mov_b32_e32 v30, v127
	v_mov_b32_e32 v29, v127
	v_mov_b32_e32 v28, v127
	v_mov_b32_e32 v27, v127
	v_mov_b32_e32 v26, v127
	v_mov_b32_e32 v17, v127
	v_mov_b32_e32 v16, v127
	v_mov_b32_e32 v15, v127
	v_mov_b32_e32 v14, v127
	v_mov_b32_e32 v13, v127
	v_mov_b32_e32 v12, v127
	v_mov_b32_e32 v11, v127
	v_mov_b32_e32 v10, v127
	v_mov_b32_e32 v57, v127
	v_mov_b32_e32 v56, v127
	v_mov_b32_e32 v55, v127
	v_mov_b32_e32 v54, v127
	v_mov_b32_e32 v53, v127
	v_mov_b32_e32 v52, v127
	v_mov_b32_e32 v51, v127
	v_mov_b32_e32 v50, v127
	v_mov_b32_e32 v41, v127
	v_mov_b32_e32 v40, v127
	v_mov_b32_e32 v39, v127
	v_mov_b32_e32 v38, v127
	v_mov_b32_e32 v37, v127
	v_mov_b32_e32 v36, v127
	v_mov_b32_e32 v35, v127
	v_mov_b32_e32 v34, v127
	v_mov_b32_e32 v25, v127
	v_mov_b32_e32 v24, v127
	v_mov_b32_e32 v23, v127
	v_mov_b32_e32 v22, v127
	v_mov_b32_e32 v21, v127
	v_mov_b32_e32 v20, v127
	v_mov_b32_e32 v19, v127
	v_mov_b32_e32 v18, v127
	v_mov_b32_e32 v9, v127
	v_mov_b32_e32 v8, v127
	v_mov_b32_e32 v7, v127
	v_mov_b32_e32 v6, v127
	v_mov_b32_e32 v5, v127
	v_mov_b32_e32 v4, v127
	v_mov_b32_e32 v3, v127
	v_mov_b32_e32 v2, v127
	s_cbranch_vccnz .LBB0_1854
	s_add_u32 s34, s34, 0x80
	s_addc_u32 s35, s35, 0
	s_add_u32 s4, s36, 0x100
	s_addc_u32 s16, s37, 0
	s_mov_b32 s17, 0
